# top-k counting probes skip key groups beyond the row length (16-key-tile granularity), counters start at the skipped count
# speedup vs baseline: 1.0199x; 1.0015x over previous
; __device__ __forceinline__ void b1_phase(const bf16* QI, const bf16* KI, const float* WI, float* SCRb  , unsigned long long* MASK,
;                                          LAS unsigned char* lds, int vcu, int G, int tid) {
;     ...
;             for (int j = 0; j < 64; ++j) { unsigned key = 0u; if (j < ntile) { const float f = srow[j * 64] + 0.0f; const unsigned bts = __float_as_uint(f); key = bts ^ ((bts >> 31) ? 0xFFFFFFFFu : 0x80000000u); } uu[j] = key; }
;             unsigned T = 1u;
;             bool exact = (limit <= 256);
;             if (limit > 256) {
;                 unsigned kmax = 0u;
; #pragma unroll
;                 for (int j = 0; j < 64; ++j) kmax = uu[j] > kmax ? uu[j] : kmax;
; #pragma unroll
;                 for (int o = 1; o < 64; o <<= 1) { const unsigned t_ = (unsigned)__shfl_xor((int)kmax, o); kmax = t_ > kmax ? t_ : kmax; }
;                 kmax = (unsigned)__builtin_amdgcn_readfirstlane((int)kmax);
;                 unsigned a = 1u, b = kmax + 1u; if (b == 0u) b = 0xFFFFFFFFu;
;                 float fa = (float)(limit - 256) + 0.5f, fb = -255.5f; int side = 0;
;                 bool done = false;
;                 if (b > 0x80000001u) {
;                     unsigned l0 = 0u, l1 = 0u, l2 = 0u, l3 = 0u; const unsigned csign = 0x80000000u;
; #pragma unroll
;                     for (int j = 0; j < 64; j += 4) cnt_lt4(l0, l1, l2, l3, uu[j], uu[j + 1], uu[j + 2], uu[j + 3], csign);
;                     const unsigned less = (l0 + l1) + (l2 + l3);
;                     const int cnt = 4096 - (int)wave_sum_u32(less);
.LBB0_661:
	s_waitcnt vmcnt(0)
	v_add_f32_e32 v2, 0, v66
	v_cmp_lt_i32_e32 vcc, -1, v2
	v_readlane_b32 s0, v251, 12
	v_mov_b32_e32 v66, 1
	v_cndmask_b32_e32 v3, -1, v239, vcc
	v_xor_b32_e32 v67, v3, v2
	s_and_b64 vcc, exec, s[6:7]
	v_readlane_b32 s1, v251, 13
	s_cbranch_vccz .LBB0_666
	v_max_u32_e32 v2, v6, v67
	v_max3_u32 v2, v8, v0, v2
	v_max3_u32 v2, v10, v4, v2
	v_max3_u32 v2, v12, v5, v2
	v_max3_u32 v2, v14, v7, v2
	v_max3_u32 v2, v15, v9, v2
	v_max3_u32 v2, v17, v11, v2
	v_max3_u32 v2, v18, v13, v2
	v_max3_u32 v2, v20, v16, v2
	v_max3_u32 v2, v22, v19, v2
	v_max3_u32 v2, v24, v21, v2
	v_max3_u32 v2, v26, v23, v2
	v_max3_u32 v2, v28, v25, v2
	v_max3_u32 v2, v30, v27, v2
	v_max3_u32 v2, v32, v29, v2
	v_max3_u32 v2, v34, v31, v2
	v_max3_u32 v2, v37, v33, v2
	v_max3_u32 v2, v39, v35, v2
	v_max3_u32 v2, v41, v36, v2
	v_max3_u32 v2, v43, v38, v2
	v_max3_u32 v2, v45, v40, v2
	v_max3_u32 v2, v47, v42, v2
	v_max3_u32 v2, v49, v44, v2
	v_max3_u32 v2, v51, v46, v2
	v_max3_u32 v2, v53, v48, v2
	v_max3_u32 v2, v55, v50, v2
	v_max3_u32 v2, v57, v52, v2
	v_max3_u32 v2, v59, v54, v2
	v_and_b32_e32 v3, 64, v238
	v_max3_u32 v2, v61, v56, v2
	v_add_u32_e32 v3, 64, v3
	v_xor_b32_e32 v66, 1, v238
	v_max3_u32 v2, v63, v58, v2
	v_cmp_lt_i32_e32 vcc, v66, v3
	v_max3_u32 v2, v64, v60, v2
	v_max3_u32 v2, v65, v62, v2
	v_cndmask_b32_e32 v66, v238, v66, vcc
	v_lshlrev_b32_e32 v66, 2, v66
	ds_bpermute_b32 v66, v66, v2
	s_mov_b32 s4, 1
	s_waitcnt lgkmcnt(0)
	v_max_u32_e32 v2, v66, v2
	v_xor_b32_e32 v66, 2, v238
	v_cmp_lt_i32_e32 vcc, v66, v3
	s_nop 1
	v_cndmask_b32_e32 v66, v238, v66, vcc
	v_lshlrev_b32_e32 v66, 2, v66
	ds_bpermute_b32 v66, v66, v2
	s_waitcnt lgkmcnt(0)
	v_max_u32_e32 v2, v66, v2
	v_xor_b32_e32 v66, 4, v238
	v_cmp_lt_i32_e32 vcc, v66, v3
	s_nop 1
	v_cndmask_b32_e32 v66, v238, v66, vcc
	v_lshlrev_b32_e32 v66, 2, v66
	ds_bpermute_b32 v66, v66, v2
	s_waitcnt lgkmcnt(0)
	v_max_u32_e32 v2, v66, v2
	v_xor_b32_e32 v66, 8, v238
	v_cmp_lt_i32_e32 vcc, v66, v3
	s_nop 1
	v_cndmask_b32_e32 v66, v238, v66, vcc
	v_lshlrev_b32_e32 v66, 2, v66
	ds_bpermute_b32 v66, v66, v2
	s_waitcnt lgkmcnt(0)
	v_max_u32_e32 v2, v66, v2
	v_xor_b32_e32 v66, 16, v238
	v_cmp_lt_i32_e32 vcc, v66, v3
	s_nop 1
	v_cndmask_b32_e32 v66, v238, v66, vcc
	v_lshlrev_b32_e32 v66, 2, v66
	ds_bpermute_b32 v66, v66, v2
	s_waitcnt lgkmcnt(0)
	v_max_u32_e32 v2, v66, v2
	v_xor_b32_e32 v66, 32, v238
	v_cmp_lt_i32_e32 vcc, v66, v3
	s_nop 1
	v_cndmask_b32_e32 v3, v238, v66, vcc
	v_lshlrev_b32_e32 v3, 2, v3
	ds_bpermute_b32 v3, v3, v2
	s_waitcnt lgkmcnt(0)
	v_max_u32_e32 v2, v3, v2
	s_nop 0
	v_readfirstlane_b32 s0, v2
	s_nop 1
	v_add_co_u32_e64 v3, s[0:1], s0, 1
	s_nop 1
	v_cndmask_b32_e64 v66, v3, -1, s[0:1]
	s_mov_b32 s0, 0x80000001
	v_cmp_lt_u32_e32 vcc, s0, v66
	s_cbranch_vccz .LBB0_668
	s_lshr_b32 s98, s99, 4
	s_lshl_b32 s98, s98, 4
	s_sub_u32 s98, 48, s98
	v_mov_b32_e32 v2, s98
	v_mov_b32_e32 v3, v1
	v_mov_b32_e32 v68, v1
	v_mov_b32_e32 v69, v1
	v_cmp_lt_u32_e64 s[0:1], v67, v239
	v_cmp_lt_u32_e64 s[2:3], v6, v239
	v_cmp_lt_u32_e64 s[4:5], v0, v239
	v_cmp_lt_u32_e64 s[6:7], v8, v239
	v_addc_co_u32_e64 v2, s[0:1], v2, 0, s[0:1]
	v_addc_co_u32_e64 v3, s[2:3], v3, 0, s[2:3]
	v_addc_co_u32_e64 v68, s[4:5], v68, 0, s[4:5]
	v_addc_co_u32_e64 v69, s[6:7], v69, 0, s[6:7]
	s_nop 0
	v_cmp_lt_u32_e64 s[0:1], v4, v239
	v_cmp_lt_u32_e64 s[2:3], v10, v239
	v_cmp_lt_u32_e64 s[4:5], v5, v239
	v_cmp_lt_u32_e64 s[6:7], v12, v239
	v_addc_co_u32_e64 v2, s[0:1], v2, 0, s[0:1]
	v_addc_co_u32_e64 v3, s[2:3], v3, 0, s[2:3]
	v_addc_co_u32_e64 v68, s[4:5], v68, 0, s[4:5]
	v_addc_co_u32_e64 v69, s[6:7], v69, 0, s[6:7]
	s_nop 0
	v_cmp_lt_u32_e64 s[0:1], v7, v239
	v_cmp_lt_u32_e64 s[2:3], v14, v239
	v_cmp_lt_u32_e64 s[4:5], v9, v239
	v_cmp_lt_u32_e64 s[6:7], v15, v239
	v_addc_co_u32_e64 v2, s[0:1], v2, 0, s[0:1]
	v_addc_co_u32_e64 v3, s[2:3], v3, 0, s[2:3]
	v_addc_co_u32_e64 v68, s[4:5], v68, 0, s[4:5]
	v_addc_co_u32_e64 v69, s[6:7], v69, 0, s[6:7]
	s_nop 0
	v_cmp_lt_u32_e64 s[0:1], v11, v239
	v_cmp_lt_u32_e64 s[2:3], v17, v239
	v_cmp_lt_u32_e64 s[4:5], v13, v239
	v_cmp_lt_u32_e64 s[6:7], v18, v239
	v_addc_co_u32_e64 v2, s[0:1], v2, 0, s[0:1]
	v_addc_co_u32_e64 v3, s[2:3], v3, 0, s[2:3]
	v_addc_co_u32_e64 v68, s[4:5], v68, 0, s[4:5]
	v_addc_co_u32_e64 v69, s[6:7], v69, 0, s[6:7]
	s_nop 0
	s_cmp_lt_u32 s99, 16
	s_cbranch_scc1 .Ltk_red_sign
; __device__ __forceinline__ void b1_phase(const bf16* QI, const bf16* KI, const float* WI, float* SCRb  , unsigned long long* MASK,
;                                          LAS unsigned char* lds, int vcu, int G, int tid) {
;     ...
;                     unsigned l0 = 0u, l1 = 0u, l2 = 0u, l3 = 0u; const unsigned csign = 0x80000000u;
; #pragma unroll
;                     for (int j = 0; j < 64; j += 4) cnt_lt4(l0, l1, l2, l3, uu[j], uu[j + 1], uu[j + 2], uu[j + 3], csign);
;                     const unsigned less = (l0 + l1) + (l2 + l3);
;                     const int cnt = 4096 - (int)wave_sum_u32(less);
;                     if (cnt == 256) { a = 0x80000000u; done = true; exact = true; }
;                     else if (cnt > 256) { a = 0x80000000u; fa = (float)(cnt - 256) + 0.5f; }
;                     else { b = 0x80000000u; fb = (float)(cnt - 256) + 0.5f; }
;                 }
	v_cmp_lt_u32_e64 s[0:1], v16, v239
	v_cmp_lt_u32_e64 s[2:3], v20, v239
	v_cmp_lt_u32_e64 s[4:5], v19, v239
	v_cmp_lt_u32_e64 s[6:7], v22, v239
	v_addc_co_u32_e64 v2, s[0:1], v2, 0, s[0:1]
	v_addc_co_u32_e64 v3, s[2:3], v3, 0, s[2:3]
	v_addc_co_u32_e64 v68, s[4:5], v68, 0, s[4:5]
	v_addc_co_u32_e64 v69, s[6:7], v69, 0, s[6:7]
	s_nop 0
	v_cmp_lt_u32_e64 s[0:1], v21, v239
	v_cmp_lt_u32_e64 s[2:3], v24, v239
	v_cmp_lt_u32_e64 s[4:5], v23, v239
	v_cmp_lt_u32_e64 s[6:7], v26, v239
	v_addc_co_u32_e64 v2, s[0:1], v2, 0, s[0:1]
	v_addc_co_u32_e64 v3, s[2:3], v3, 0, s[2:3]
	v_addc_co_u32_e64 v68, s[4:5], v68, 0, s[4:5]
	v_addc_co_u32_e64 v69, s[6:7], v69, 0, s[6:7]
	s_nop 0
	v_cmp_lt_u32_e64 s[0:1], v25, v239
	v_cmp_lt_u32_e64 s[2:3], v28, v239
	v_cmp_lt_u32_e64 s[4:5], v27, v239
	v_cmp_lt_u32_e64 s[6:7], v30, v239
	v_addc_co_u32_e64 v2, s[0:1], v2, 0, s[0:1]
	v_addc_co_u32_e64 v3, s[2:3], v3, 0, s[2:3]
	v_addc_co_u32_e64 v68, s[4:5], v68, 0, s[4:5]
	v_addc_co_u32_e64 v69, s[6:7], v69, 0, s[6:7]
	s_nop 0
	v_cmp_lt_u32_e64 s[0:1], v29, v239
	v_cmp_lt_u32_e64 s[2:3], v32, v239
	v_cmp_lt_u32_e64 s[4:5], v31, v239
	v_cmp_lt_u32_e64 s[6:7], v34, v239
	v_addc_co_u32_e64 v2, s[0:1], v2, 0, s[0:1]
	v_addc_co_u32_e64 v3, s[2:3], v3, 0, s[2:3]
	v_addc_co_u32_e64 v68, s[4:5], v68, 0, s[4:5]
	v_addc_co_u32_e64 v69, s[6:7], v69, 0, s[6:7]
	s_nop 0
	s_cmp_lt_u32 s99, 32
	s_cbranch_scc1 .Ltk_red_sign
	v_cmp_lt_u32_e64 s[0:1], v33, v239
	v_cmp_lt_u32_e64 s[2:3], v37, v239
	v_cmp_lt_u32_e64 s[4:5], v35, v239
	v_cmp_lt_u32_e64 s[6:7], v39, v239
	v_addc_co_u32_e64 v2, s[0:1], v2, 0, s[0:1]
	v_addc_co_u32_e64 v3, s[2:3], v3, 0, s[2:3]
	v_addc_co_u32_e64 v68, s[4:5], v68, 0, s[4:5]
	v_addc_co_u32_e64 v69, s[6:7], v69, 0, s[6:7]
	s_nop 0
	v_cmp_lt_u32_e64 s[0:1], v36, v239
	v_cmp_lt_u32_e64 s[2:3], v41, v239
	v_cmp_lt_u32_e64 s[4:5], v38, v239
	v_cmp_lt_u32_e64 s[6:7], v43, v239
	v_addc_co_u32_e64 v2, s[0:1], v2, 0, s[0:1]
	v_addc_co_u32_e64 v3, s[2:3], v3, 0, s[2:3]
	v_addc_co_u32_e64 v68, s[4:5], v68, 0, s[4:5]
	v_addc_co_u32_e64 v69, s[6:7], v69, 0, s[6:7]
	s_nop 0
	v_cmp_lt_u32_e64 s[0:1], v40, v239
	v_cmp_lt_u32_e64 s[2:3], v45, v239
	v_cmp_lt_u32_e64 s[4:5], v42, v239
	v_cmp_lt_u32_e64 s[6:7], v47, v239
	v_addc_co_u32_e64 v2, s[0:1], v2, 0, s[0:1]
	v_addc_co_u32_e64 v3, s[2:3], v3, 0, s[2:3]
	v_addc_co_u32_e64 v68, s[4:5], v68, 0, s[4:5]
	v_addc_co_u32_e64 v69, s[6:7], v69, 0, s[6:7]
	s_nop 0
	v_cmp_lt_u32_e64 s[0:1], v44, v239
	v_cmp_lt_u32_e64 s[2:3], v49, v239
	v_cmp_lt_u32_e64 s[4:5], v46, v239
	v_cmp_lt_u32_e64 s[6:7], v51, v239
	v_addc_co_u32_e64 v2, s[0:1], v2, 0, s[0:1]
	v_addc_co_u32_e64 v3, s[2:3], v3, 0, s[2:3]
	v_addc_co_u32_e64 v68, s[4:5], v68, 0, s[4:5]
	v_addc_co_u32_e64 v69, s[6:7], v69, 0, s[6:7]
	s_nop 0
	s_cmp_lt_u32 s99, 48
	s_cbranch_scc1 .Ltk_red_sign
	v_cmp_lt_u32_e64 s[0:1], v48, v239
	v_cmp_lt_u32_e64 s[2:3], v53, v239
	v_cmp_lt_u32_e64 s[4:5], v50, v239
	v_cmp_lt_u32_e64 s[6:7], v55, v239
	v_addc_co_u32_e64 v2, s[0:1], v2, 0, s[0:1]
	v_addc_co_u32_e64 v3, s[2:3], v3, 0, s[2:3]
	v_addc_co_u32_e64 v68, s[4:5], v68, 0, s[4:5]
	v_addc_co_u32_e64 v69, s[6:7], v69, 0, s[6:7]
	s_nop 0
	v_cmp_lt_u32_e64 s[0:1], v52, v239
	v_cmp_lt_u32_e64 s[2:3], v57, v239
	v_cmp_lt_u32_e64 s[4:5], v54, v239
	v_cmp_lt_u32_e64 s[6:7], v59, v239
	v_addc_co_u32_e64 v2, s[0:1], v2, 0, s[0:1]
	v_addc_co_u32_e64 v3, s[2:3], v3, 0, s[2:3]
	v_addc_co_u32_e64 v68, s[4:5], v68, 0, s[4:5]
	v_addc_co_u32_e64 v69, s[6:7], v69, 0, s[6:7]
	s_nop 0
	v_cmp_lt_u32_e64 s[0:1], v56, v239
	v_cmp_lt_u32_e64 s[2:3], v61, v239
	v_cmp_lt_u32_e64 s[4:5], v58, v239
	v_cmp_lt_u32_e64 s[6:7], v63, v239
	v_addc_co_u32_e64 v2, s[0:1], v2, 0, s[0:1]
	v_addc_co_u32_e64 v3, s[2:3], v3, 0, s[2:3]
	v_addc_co_u32_e64 v68, s[4:5], v68, 0, s[4:5]
	v_addc_co_u32_e64 v69, s[6:7], v69, 0, s[6:7]
	s_nop 0
	v_cmp_lt_u32_e64 s[0:1], v60, v239
	v_cmp_lt_u32_e64 s[2:3], v64, v239
	v_cmp_lt_u32_e64 s[4:5], v62, v239
	v_cmp_lt_u32_e64 s[6:7], v65, v239
	v_addc_co_u32_e64 v2, s[0:1], v2, 0, s[0:1]
	v_addc_co_u32_e64 v3, s[2:3], v3, 0, s[2:3]
	v_addc_co_u32_e64 v68, s[4:5], v68, 0, s[4:5]
	v_addc_co_u32_e64 v69, s[6:7], v69, 0, s[6:7]
.Ltk_red_sign:
	s_brev_b32 s4, 1
	v_add_u32_e32 v2, v3, v2
	v_add3_u32 v2, v2, v68, v69
	s_nop 1
	v_add_u32_dpp v2, v2, v2 row_shr:1 row_mask:0xf bank_mask:0xf bound_ctrl:1
	s_nop 1
	v_add_u32_dpp v2, v2, v2 row_shr:2 row_mask:0xf bank_mask:0xf bound_ctrl:1
	s_nop 1
	v_add_u32_dpp v2, v2, v2 row_shr:4 row_mask:0xf bank_mask:0xf bound_ctrl:1
	s_nop 1
	v_add_u32_dpp v2, v2, v2 row_shr:8 row_mask:0xf bank_mask:0xf bound_ctrl:1
	s_nop 1
	v_add_u32_dpp v2, v2, v2 row_bcast:15 row_mask:0xa bank_mask:0xf
	s_nop 1
	v_add_u32_dpp v2, v2, v2 row_bcast:31 row_mask:0xc bank_mask:0xf
	s_nop 0
	v_readlane_b32 s0, v2, 63
	s_cmpk_eq_i32 s0, 0xf00
	s_cbranch_scc1 .LBB0_689
	s_sub_i32 s5, 0xf00, s0
	s_cmpk_lt_i32 s0, 0xf00
	s_cbranch_scc1 .LBB0_690
	v_cvt_f32_i32_e32 v2, s5
	s_mov_b32 s4, 1
	v_bfrev_b32_e32 v66, 1
	v_readlane_b32 s5, v251, 14
	v_add_f32_e32 v2, 0.5, v2
	s_branch .LBB0_691

; __device__ __forceinline__ void b1_phase(const bf16* QI, const bf16* KI, const float* WI, float* SCRb  , unsigned long long* MASK,
;                                          LAS unsigned char* lds, int vcu, int G, int tid) {
;     ...
;                 for (int iter = 0; iter < 64 && !done; ++iter) {
;                     if (b - a <= 1u) break;
;                     unsigned c;
;                     if (iter < 12) { const float t = fa * __builtin_amdgcn_rcpf(fa - fb); c = a + (unsigned)(t * (float)(b - a)); if (c <= a) c = a + 1u; if (c >= b) c = b - 1u; }
;                     else c = a + ((b - a) >> 1);
;                     unsigned l0 = 0u, l1 = 0u, l2 = 0u, l3 = 0u;
; #pragma unroll
;                     for (int j = 0; j < 64; j += 4) cnt_lt4(l0, l1, l2, l3, uu[j], uu[j + 1], uu[j + 2], uu[j + 3], c);
;                     const unsigned less = (l0 + l1) + (l2 + l3);
;                     const int cnt = 4096 - (int)wave_sum_u32(less);
;                     if (cnt == 256) { a = c; exact = true; break; }
;                     if (cnt > 256) { a = c; fa = (float)(cnt - 256) + 0.5f; if (side > 0) fb *= 0.5f; side = 1; }
;                     else { b = c; fb = (float)(cnt - 256) + 0.5f; if (side < 0) fa *= 0.5f; side = -1; }
.LBB0_676:
	s_lshr_b32 s98, s99, 4
	s_lshl_b32 s98, s98, 4
	s_sub_u32 s98, 48, s98
	v_mov_b32_e32 v70, s98
	v_mov_b32_e32 v71, 0
	v_mov_b32_e32 v72, 0
	v_mov_b32_e32 v73, 0
	v_cmp_lt_u32_e64 s[2:3], v67, v69
	v_cmp_lt_u32_e64 s[4:5], v6, v69
	v_cmp_lt_u32_e64 s[8:9], v0, v69
	v_cmp_lt_u32_e64 s[10:11], v8, v69
	v_addc_co_u32_e64 v70, s[2:3], v70, 0, s[2:3]
	v_addc_co_u32_e64 v71, s[4:5], v71, 0, s[4:5]
	v_addc_co_u32_e64 v72, s[8:9], v72, 0, s[8:9]
	v_addc_co_u32_e64 v73, s[10:11], v73, 0, s[10:11]
	s_nop 0
	v_cmp_lt_u32_e64 s[2:3], v4, v69
	v_cmp_lt_u32_e64 s[4:5], v10, v69
	v_cmp_lt_u32_e64 s[8:9], v5, v69
	v_cmp_lt_u32_e64 s[10:11], v12, v69
	v_addc_co_u32_e64 v70, s[2:3], v70, 0, s[2:3]
	v_addc_co_u32_e64 v71, s[4:5], v71, 0, s[4:5]
	v_addc_co_u32_e64 v72, s[8:9], v72, 0, s[8:9]
	v_addc_co_u32_e64 v73, s[10:11], v73, 0, s[10:11]
	s_nop 0
	v_cmp_lt_u32_e64 s[2:3], v7, v69
	v_cmp_lt_u32_e64 s[4:5], v14, v69
	v_cmp_lt_u32_e64 s[8:9], v9, v69
	v_cmp_lt_u32_e64 s[10:11], v15, v69
	v_addc_co_u32_e64 v70, s[2:3], v70, 0, s[2:3]
	v_addc_co_u32_e64 v71, s[4:5], v71, 0, s[4:5]
	v_addc_co_u32_e64 v72, s[8:9], v72, 0, s[8:9]
	v_addc_co_u32_e64 v73, s[10:11], v73, 0, s[10:11]
	s_nop 0
	v_cmp_lt_u32_e64 s[2:3], v11, v69
	v_cmp_lt_u32_e64 s[4:5], v17, v69
	v_cmp_lt_u32_e64 s[8:9], v13, v69
	v_cmp_lt_u32_e64 s[10:11], v18, v69
	v_addc_co_u32_e64 v70, s[2:3], v70, 0, s[2:3]
	v_addc_co_u32_e64 v71, s[4:5], v71, 0, s[4:5]
	v_addc_co_u32_e64 v72, s[8:9], v72, 0, s[8:9]
	v_addc_co_u32_e64 v73, s[10:11], v73, 0, s[10:11]
	s_nop 0
	s_cmp_lt_u32 s99, 16
	s_cbranch_scc1 .Ltk_red_loop
	v_cmp_lt_u32_e64 s[2:3], v16, v69
	v_cmp_lt_u32_e64 s[4:5], v20, v69
	v_cmp_lt_u32_e64 s[8:9], v19, v69
	v_cmp_lt_u32_e64 s[10:11], v22, v69
	v_addc_co_u32_e64 v70, s[2:3], v70, 0, s[2:3]
	v_addc_co_u32_e64 v71, s[4:5], v71, 0, s[4:5]
	v_addc_co_u32_e64 v72, s[8:9], v72, 0, s[8:9]
	v_addc_co_u32_e64 v73, s[10:11], v73, 0, s[10:11]
	s_nop 0
	v_cmp_lt_u32_e64 s[2:3], v21, v69
	v_cmp_lt_u32_e64 s[4:5], v24, v69
	v_cmp_lt_u32_e64 s[8:9], v23, v69
	v_cmp_lt_u32_e64 s[10:11], v26, v69
	v_addc_co_u32_e64 v70, s[2:3], v70, 0, s[2:3]
	v_addc_co_u32_e64 v71, s[4:5], v71, 0, s[4:5]
	v_addc_co_u32_e64 v72, s[8:9], v72, 0, s[8:9]
	v_addc_co_u32_e64 v73, s[10:11], v73, 0, s[10:11]
	s_nop 0
	v_cmp_lt_u32_e64 s[2:3], v25, v69
	v_cmp_lt_u32_e64 s[4:5], v28, v69
	v_cmp_lt_u32_e64 s[8:9], v27, v69
	v_cmp_lt_u32_e64 s[10:11], v30, v69
	v_addc_co_u32_e64 v70, s[2:3], v70, 0, s[2:3]
	v_addc_co_u32_e64 v71, s[4:5], v71, 0, s[4:5]
	v_addc_co_u32_e64 v72, s[8:9], v72, 0, s[8:9]
	v_addc_co_u32_e64 v73, s[10:11], v73, 0, s[10:11]
	s_nop 0
	v_cmp_lt_u32_e64 s[2:3], v29, v69
	v_cmp_lt_u32_e64 s[4:5], v32, v69
	v_cmp_lt_u32_e64 s[8:9], v31, v69
	v_cmp_lt_u32_e64 s[10:11], v34, v69
	v_addc_co_u32_e64 v70, s[2:3], v70, 0, s[2:3]
	v_addc_co_u32_e64 v71, s[4:5], v71, 0, s[4:5]
	v_addc_co_u32_e64 v72, s[8:9], v72, 0, s[8:9]
	v_addc_co_u32_e64 v73, s[10:11], v73, 0, s[10:11]
	s_nop 0
	s_cmp_lt_u32 s99, 32
	s_cbranch_scc1 .Ltk_red_loop
	v_cmp_lt_u32_e64 s[2:3], v33, v69
	v_cmp_lt_u32_e64 s[4:5], v37, v69
	v_cmp_lt_u32_e64 s[8:9], v35, v69
	v_cmp_lt_u32_e64 s[10:11], v39, v69
	v_addc_co_u32_e64 v70, s[2:3], v70, 0, s[2:3]
	v_addc_co_u32_e64 v71, s[4:5], v71, 0, s[4:5]
	v_addc_co_u32_e64 v72, s[8:9], v72, 0, s[8:9]
	v_addc_co_u32_e64 v73, s[10:11], v73, 0, s[10:11]
	s_nop 0
	v_cmp_lt_u32_e64 s[2:3], v36, v69
	v_cmp_lt_u32_e64 s[4:5], v41, v69
	v_cmp_lt_u32_e64 s[8:9], v38, v69
	v_cmp_lt_u32_e64 s[10:11], v43, v69
	v_addc_co_u32_e64 v70, s[2:3], v70, 0, s[2:3]
	v_addc_co_u32_e64 v71, s[4:5], v71, 0, s[4:5]
	v_addc_co_u32_e64 v72, s[8:9], v72, 0, s[8:9]
	v_addc_co_u32_e64 v73, s[10:11], v73, 0, s[10:11]
	s_nop 0
	v_cmp_lt_u32_e64 s[2:3], v40, v69
	v_cmp_lt_u32_e64 s[4:5], v45, v69
	v_cmp_lt_u32_e64 s[8:9], v42, v69
	v_cmp_lt_u32_e64 s[10:11], v47, v69
	v_addc_co_u32_e64 v70, s[2:3], v70, 0, s[2:3]
	v_addc_co_u32_e64 v71, s[4:5], v71, 0, s[4:5]
	v_addc_co_u32_e64 v72, s[8:9], v72, 0, s[8:9]
	v_addc_co_u32_e64 v73, s[10:11], v73, 0, s[10:11]
	s_nop 0
	v_cmp_lt_u32_e64 s[2:3], v44, v69
	v_cmp_lt_u32_e64 s[4:5], v49, v69
	v_cmp_lt_u32_e64 s[8:9], v46, v69
	v_cmp_lt_u32_e64 s[10:11], v51, v69
	v_addc_co_u32_e64 v70, s[2:3], v70, 0, s[2:3]
	v_addc_co_u32_e64 v71, s[4:5], v71, 0, s[4:5]
	v_addc_co_u32_e64 v72, s[8:9], v72, 0, s[8:9]
	v_addc_co_u32_e64 v73, s[10:11], v73, 0, s[10:11]
	s_nop 0
	s_cmp_lt_u32 s99, 48
	s_cbranch_scc1 .Ltk_red_loop
	v_cmp_lt_u32_e64 s[2:3], v48, v69
	v_cmp_lt_u32_e64 s[4:5], v53, v69
	v_cmp_lt_u32_e64 s[8:9], v50, v69
	v_cmp_lt_u32_e64 s[10:11], v55, v69
	v_addc_co_u32_e64 v70, s[2:3], v70, 0, s[2:3]
	v_addc_co_u32_e64 v71, s[4:5], v71, 0, s[4:5]
	v_addc_co_u32_e64 v72, s[8:9], v72, 0, s[8:9]
	v_addc_co_u32_e64 v73, s[10:11], v73, 0, s[10:11]
	s_nop 0
	v_cmp_lt_u32_e64 s[2:3], v52, v69
	v_cmp_lt_u32_e64 s[4:5], v57, v69
	v_cmp_lt_u32_e64 s[8:9], v54, v69
	v_cmp_lt_u32_e64 s[10:11], v59, v69
	v_addc_co_u32_e64 v70, s[2:3], v70, 0, s[2:3]
	v_addc_co_u32_e64 v71, s[4:5], v71, 0, s[4:5]
	v_addc_co_u32_e64 v72, s[8:9], v72, 0, s[8:9]
	v_addc_co_u32_e64 v73, s[10:11], v73, 0, s[10:11]
	s_nop 0
	v_cmp_lt_u32_e64 s[2:3], v56, v69
	v_cmp_lt_u32_e64 s[4:5], v61, v69
	v_cmp_lt_u32_e64 s[8:9], v58, v69
	v_cmp_lt_u32_e64 s[10:11], v63, v69
	v_addc_co_u32_e64 v70, s[2:3], v70, 0, s[2:3]
	v_addc_co_u32_e64 v71, s[4:5], v71, 0, s[4:5]
	v_addc_co_u32_e64 v72, s[8:9], v72, 0, s[8:9]
	v_addc_co_u32_e64 v73, s[10:11], v73, 0, s[10:11]
	s_nop 0
	v_cmp_lt_u32_e64 s[2:3], v60, v69
	v_cmp_lt_u32_e64 s[4:5], v64, v69
	v_cmp_lt_u32_e64 s[8:9], v62, v69
	v_cmp_lt_u32_e64 s[10:11], v65, v69
	v_addc_co_u32_e64 v70, s[2:3], v70, 0, s[2:3]
	v_addc_co_u32_e64 v71, s[4:5], v71, 0, s[4:5]
	v_addc_co_u32_e64 v72, s[8:9], v72, 0, s[8:9]
	v_addc_co_u32_e64 v73, s[10:11], v73, 0, s[10:11]
	s_nop 0
.Ltk_red_loop:
	v_add_u32_e32 v70, v71, v70
	v_add3_u32 v70, v70, v72, v73
	s_nop 1
	v_add_u32_dpp v70, v70, v70 row_shr:1 row_mask:0xf bank_mask:0xf bound_ctrl:1
	s_nop 1
	v_add_u32_dpp v70, v70, v70 row_shr:2 row_mask:0xf bank_mask:0xf bound_ctrl:1
	s_nop 1
	v_add_u32_dpp v70, v70, v70 row_shr:4 row_mask:0xf bank_mask:0xf bound_ctrl:1
	s_nop 1
	v_add_u32_dpp v70, v70, v70 row_shr:8 row_mask:0xf bank_mask:0xf bound_ctrl:1
	s_nop 1
	v_add_u32_dpp v70, v70, v70 row_bcast:15 row_mask:0xa bank_mask:0xf
	s_nop 1
	v_add_u32_dpp v70, v70, v70 row_bcast:31 row_mask:0xc bank_mask:0xf
	s_nop 0
	v_readlane_b32 s4, v70, 63
	s_cmpk_lg_i32 s4, 0xf00
	s_cselect_b64 s[2:3], -1, 0
	s_cmpk_eq_i32 s4, 0xf00
	s_cbranch_scc1 .LBB0_679
	s_sub_i32 s8, 0xf00, s4
	s_cmpk_gt_i32 s4, 0xeff
	s_cbranch_scc0 .LBB0_680
	v_cvt_f32_i32_e32 v70, s8
	s_cmp_lt_i32 s7, 0
	s_cselect_b64 vcc, -1, 0
	v_mul_f32_e32 v71, 0.5, v68
	v_add_f32_e32 v70, 0.5, v70
	v_cndmask_b32_e32 v68, v68, v71, vcc
	s_mov_b32 s9, -1
	v_mov_b32_e32 v71, v69
	s_cbranch_execz .LBB0_681
	s_branch .LBB0_682
